# v51 + hipcc's vmcnt(0) drain in the per-unit accumulator zero-init removed (gates, lru-out, qkv GEMMs): the K-loop's counted waits cover the DMAs
# speedup vs baseline: 1.0027x; 1.0027x over previous
; template <class Epi, class Sched, bool ALIGN_EPI = false, bool SP2 = false>
; __device__ __forceinline__ void gemm_phase(PG8_LAS unsigned char* lds, const Gemm g, const Sched& S, const Epi& E, const int wv) {
;     ...
; #pragma unroll
;         for (int a = 0; a < 2; ++a)
; #pragma unroll
;             for (int b = 0; b < 2; ++b)
; #pragma unroll
;                 for (int m = 0; m < 4; ++m)
; #pragma unroll
;                     for (int n = 0; n < 2; ++n) acc[a][b][m][n] = (f32x4){0.f, 0.f, 0.f, 0.f};
;         cur = nxt; cA = nA; cB = nB; ++ui;
.LBB0_334:
	v_mov_b32_e32 v141, 0
	s_andn2_b64 vcc, exec, s[34:35]
	v_mov_b32_e32 v140, v141
	v_mov_b32_e32 v139, v141
	v_mov_b32_e32 v138, v141
	v_mov_b32_e32 v145, v141
	v_mov_b32_e32 v144, v141
	v_mov_b32_e32 v143, v141
	v_mov_b32_e32 v142, v141
	v_mov_b32_e32 v129, v141
	v_mov_b32_e32 v128, v141
	v_mov_b32_e32 v127, v141
	v_mov_b32_e32 v126, v141
	v_mov_b32_e32 v125, v141
	v_mov_b32_e32 v124, v141
	v_mov_b32_e32 v123, v141
	v_mov_b32_e32 v122, v141
	v_mov_b32_e32 v113, v141
	v_mov_b32_e32 v112, v141
	v_mov_b32_e32 v111, v141
	v_mov_b32_e32 v110, v141
	v_mov_b32_e32 v109, v141
	v_mov_b32_e32 v108, v141
	v_mov_b32_e32 v107, v141
	v_mov_b32_e32 v106, v141
	v_mov_b32_e32 v97, v141
	v_mov_b32_e32 v96, v141
	v_mov_b32_e32 v95, v141
	v_mov_b32_e32 v94, v141
	v_mov_b32_e32 v93, v141
	v_mov_b32_e32 v92, v141
	v_mov_b32_e32 v91, v141
	v_mov_b32_e32 v90, v141
	v_mov_b32_e32 v137, v141
	v_mov_b32_e32 v136, v141
	v_mov_b32_e32 v135, v141
	v_mov_b32_e32 v134, v141
	v_mov_b32_e32 v133, v141
	v_mov_b32_e32 v132, v141
	v_mov_b32_e32 v131, v141
	v_mov_b32_e32 v130, v141
	v_mov_b32_e32 v121, v141
	v_mov_b32_e32 v120, v141
	v_mov_b32_e32 v119, v141
	v_mov_b32_e32 v118, v141
	v_mov_b32_e32 v117, v141
	v_mov_b32_e32 v116, v141
	v_mov_b32_e32 v115, v141
	v_mov_b32_e32 v114, v141
	v_mov_b32_e32 v105, v141
	v_mov_b32_e32 v104, v141
	v_mov_b32_e32 v103, v141
	v_mov_b32_e32 v102, v141
	v_mov_b32_e32 v101, v141
	v_mov_b32_e32 v100, v141
	v_mov_b32_e32 v99, v141
	v_mov_b32_e32 v98, v141
	v_mov_b32_e32 v89, v141
	v_mov_b32_e32 v88, v141
	v_mov_b32_e32 v87, v141
	v_mov_b32_e32 v86, v141
	v_mov_b32_e32 v85, v141
	v_mov_b32_e32 v84, v141
	v_mov_b32_e32 v83, v141
	v_mov_b32_e32 v82, v141
	v_mov_b32_e32 v81, v141
	v_mov_b32_e32 v80, v141
	v_mov_b32_e32 v79, v141
	v_mov_b32_e32 v78, v141
	v_mov_b32_e32 v77, v141
	v_mov_b32_e32 v76, v141
	v_mov_b32_e32 v75, v141
	v_mov_b32_e32 v74, v141
	v_mov_b32_e32 v65, v141
	v_mov_b32_e32 v64, v141
	v_mov_b32_e32 v63, v141
	v_mov_b32_e32 v62, v141
	v_mov_b32_e32 v61, v141
	v_mov_b32_e32 v60, v141
	v_mov_b32_e32 v59, v141
	s_nop 0
	v_mov_b32_e32 v58, v141
	v_mov_b32_e32 v41, v141
	v_mov_b32_e32 v40, v141
	v_mov_b32_e32 v39, v141
	v_mov_b32_e32 v38, v141
	v_mov_b32_e32 v37, v141
	v_mov_b32_e32 v36, v141
	v_mov_b32_e32 v35, v141
	v_mov_b32_e32 v34, v141
	v_mov_b32_e32 v17, v141
	v_mov_b32_e32 v16, v141
	v_mov_b32_e32 v15, v141
	v_mov_b32_e32 v14, v141
	v_mov_b32_e32 v13, v141
	v_mov_b32_e32 v12, v141
	v_mov_b32_e32 v11, v141
	v_mov_b32_e32 v10, v141
	v_mov_b32_e32 v73, v141
	v_mov_b32_e32 v72, v141
	v_mov_b32_e32 v71, v141
	v_mov_b32_e32 v70, v141
	v_mov_b32_e32 v69, v141
	v_mov_b32_e32 v68, v141
	v_mov_b32_e32 v67, v141
	v_mov_b32_e32 v66, v141
	v_mov_b32_e32 v57, v141
	v_mov_b32_e32 v56, v141
	v_mov_b32_e32 v55, v141
	v_mov_b32_e32 v54, v141
	v_mov_b32_e32 v53, v141
	v_mov_b32_e32 v52, v141
	v_mov_b32_e32 v51, v141
	v_mov_b32_e32 v50, v141
	v_mov_b32_e32 v25, v141
	v_mov_b32_e32 v24, v141
	v_mov_b32_e32 v23, v141
	v_mov_b32_e32 v22, v141
	v_mov_b32_e32 v21, v141
	v_mov_b32_e32 v20, v141
	v_mov_b32_e32 v19, v141
	v_mov_b32_e32 v18, v141
	v_mov_b32_e32 v9, v141
	v_mov_b32_e32 v8, v141
	v_mov_b32_e32 v7, v141
	v_mov_b32_e32 v6, v141
	v_mov_b32_e32 v5, v141
	v_mov_b32_e32 v4, v141
	v_mov_b32_e32 v3, v141
	v_mov_b32_e32 v2, v141
	s_cbranch_vccnz .LBB0_337
	s_add_u32 s12, s40, 0x80080
	s_addc_u32 s13, s41, 0
	s_add_u32 s11, s14, 0x100
	v_mov_b32_e32 v2, 0
	s_addc_u32 s17, s15, 0
	s_mov_b32 s14, 0
	v_mov_b32_e32 v3, v2
	v_mov_b32_e32 v4, v2
	v_mov_b32_e32 v5, v2
	v_mov_b32_e32 v6, v2
	v_mov_b32_e32 v7, v2
	v_mov_b32_e32 v8, v2
	v_mov_b32_e32 v9, v2
	v_mov_b32_e32 v18, v2
	v_mov_b32_e32 v19, v2
	v_mov_b32_e32 v20, v2
	v_mov_b32_e32 v21, v2
	v_mov_b32_e32 v22, v2
	v_mov_b32_e32 v23, v2
	v_mov_b32_e32 v24, v2
	v_mov_b32_e32 v25, v2
	v_mov_b32_e32 v50, v2
	v_mov_b32_e32 v51, v2
	v_mov_b32_e32 v52, v2
	v_mov_b32_e32 v53, v2
	v_mov_b32_e32 v54, v2
	v_mov_b32_e32 v55, v2
	v_mov_b32_e32 v56, v2
	v_mov_b32_e32 v57, v2
	v_mov_b32_e32 v66, v2
	v_mov_b32_e32 v67, v2
	v_mov_b32_e32 v68, v2
	v_mov_b32_e32 v69, v2
	v_mov_b32_e32 v70, v2
	v_mov_b32_e32 v71, v2
	v_mov_b32_e32 v72, v2
	v_mov_b32_e32 v73, v2
	v_mov_b32_e32 v10, v2
	v_mov_b32_e32 v11, v2
	v_mov_b32_e32 v12, v2
	v_mov_b32_e32 v13, v2
	v_mov_b32_e32 v14, v2
	v_mov_b32_e32 v15, v2
	v_mov_b32_e32 v16, v2
	v_mov_b32_e32 v17, v2
	v_mov_b32_e32 v34, v2
	v_mov_b32_e32 v35, v2
	v_mov_b32_e32 v36, v2
	v_mov_b32_e32 v37, v2
	v_mov_b32_e32 v38, v2
	v_mov_b32_e32 v39, v2
	v_mov_b32_e32 v40, v2
	v_mov_b32_e32 v41, v2
	v_mov_b32_e32 v58, v2
	v_mov_b32_e32 v59, v2
	v_mov_b32_e32 v60, v2
	v_mov_b32_e32 v61, v2
	v_mov_b32_e32 v62, v2
	v_mov_b32_e32 v63, v2
	v_mov_b32_e32 v64, v2
	v_mov_b32_e32 v65, v2
	v_mov_b32_e32 v74, v2
	v_mov_b32_e32 v75, v2
	v_mov_b32_e32 v76, v2
	v_mov_b32_e32 v77, v2
	v_mov_b32_e32 v78, v2
	v_mov_b32_e32 v79, v2
	v_mov_b32_e32 v80, v2
	v_mov_b32_e32 v81, v2
	v_mov_b32_e32 v82, v2
	v_mov_b32_e32 v83, v2
	v_mov_b32_e32 v84, v2
	v_mov_b32_e32 v85, v2
	v_mov_b32_e32 v86, v2
	v_mov_b32_e32 v87, v2
	v_mov_b32_e32 v88, v2
	v_mov_b32_e32 v89, v2
	v_mov_b32_e32 v98, v2
	v_mov_b32_e32 v99, v2
	v_mov_b32_e32 v100, v2
	v_mov_b32_e32 v101, v2
	v_mov_b32_e32 v102, v2
	v_mov_b32_e32 v103, v2
	v_mov_b32_e32 v104, v2
	v_mov_b32_e32 v105, v2
	v_mov_b32_e32 v114, v2
	v_mov_b32_e32 v115, v2
	v_mov_b32_e32 v116, v2
	v_mov_b32_e32 v117, v2
	v_mov_b32_e32 v118, v2
	v_mov_b32_e32 v119, v2
	v_mov_b32_e32 v120, v2
	v_mov_b32_e32 v121, v2
	v_mov_b32_e32 v130, v2
	v_mov_b32_e32 v131, v2
	v_mov_b32_e32 v132, v2
	v_mov_b32_e32 v133, v2
	v_mov_b32_e32 v134, v2
	v_mov_b32_e32 v135, v2
	v_mov_b32_e32 v136, v2
	v_mov_b32_e32 v137, v2
	v_mov_b32_e32 v90, v2
	v_mov_b32_e32 v91, v2
	v_mov_b32_e32 v92, v2
	v_mov_b32_e32 v93, v2
	v_mov_b32_e32 v94, v2
	v_mov_b32_e32 v95, v2
	v_mov_b32_e32 v96, v2
	v_mov_b32_e32 v97, v2
	v_mov_b32_e32 v106, v2
	v_mov_b32_e32 v107, v2
	v_mov_b32_e32 v108, v2
	v_mov_b32_e32 v109, v2
	v_mov_b32_e32 v110, v2
	v_mov_b32_e32 v111, v2
	v_mov_b32_e32 v112, v2
	v_mov_b32_e32 v113, v2
	v_mov_b32_e32 v122, v2
	v_mov_b32_e32 v123, v2
	v_mov_b32_e32 v124, v2
	v_mov_b32_e32 v125, v2
	v_mov_b32_e32 v126, v2
	v_mov_b32_e32 v127, v2
	v_mov_b32_e32 v128, v2
	v_mov_b32_e32 v129, v2
	v_mov_b32_e32 v142, v2
	v_mov_b32_e32 v143, v2
	v_mov_b32_e32 v144, v2
	v_mov_b32_e32 v145, v2
	v_mov_b32_e32 v138, v2
	v_mov_b32_e32 v139, v2
	v_mov_b32_e32 v140, v2
	v_mov_b32_e32 v141, v2

;     __host__ __device__ bool next(int i, Unit& u) const { const int P = (i >> 1) * G + c; if (P >= 256) return false; u.pm = P >> 3; u.pn = (P & 7) + 8 * (i & 1); return true; }
; template <class Epi, class Sched, bool ALIGN_EPI = false, bool SP2 = false>
; __device__ __forceinline__ void gemm_phase(PG8_LAS unsigned char* lds, const Gemm g, const Sched& S, const Epi& E, const int wv) {
;     ...
;         const bool has_next = S.next(ui + 1, nxt);
;         const char* nA = has_next ? (const char*)g.A + (size_t)nxt.pm * tstepA + (g.amod ? (size_t)(nxt.pn % g.amod) * K * 2 : (size_t)0) : cA; const char* nB = has_next ? (const char*)g.Bt + (size_t)nxt.pn * tstepB : cB;
;     ...
; #pragma unroll
;         for (int a = 0; a < 2; ++a)
; #pragma unroll
;             for (int b = 0; b < 2; ++b)
; #pragma unroll
;                 for (int m = 0; m < 4; ++m)
; #pragma unroll
;                     for (int n = 0; n < 2; ++n) acc[a][b][m][n] = (f32x4){0.f, 0.f, 0.f, 0.f};
;         cur = nxt; cA = nA; cB = nB; ++ui;
.LBB0_671:
	s_ashr_i32 s89, s88, 31
	s_lshl_b64 s[14:15], s[88:89], 20
	s_add_u32 s14, s17, s14
	v_mov_b32_e32 v137, 0
	s_addc_u32 s15, s19, s15
	s_andn2_b64 vcc, exec, s[10:11]
	v_mov_b32_e32 v136, v137
	v_mov_b32_e32 v135, v137
	v_mov_b32_e32 v134, v137
	v_mov_b32_e32 v133, v137
	v_mov_b32_e32 v132, v137
	v_mov_b32_e32 v131, v137
	v_mov_b32_e32 v130, v137
	v_mov_b32_e32 v113, v137
	v_mov_b32_e32 v112, v137
	v_mov_b32_e32 v111, v137
	v_mov_b32_e32 v110, v137
	v_mov_b32_e32 v109, v137
	v_mov_b32_e32 v108, v137
	v_mov_b32_e32 v107, v137
	v_mov_b32_e32 v106, v137
	v_mov_b32_e32 v97, v137
	v_mov_b32_e32 v96, v137
	v_mov_b32_e32 v95, v137
	v_mov_b32_e32 v94, v137
	v_mov_b32_e32 v93, v137
	v_mov_b32_e32 v92, v137
	v_mov_b32_e32 v91, v137
	v_mov_b32_e32 v90, v137
	v_mov_b32_e32 v81, v137
	v_mov_b32_e32 v80, v137
	v_mov_b32_e32 v79, v137
	v_mov_b32_e32 v78, v137
	v_mov_b32_e32 v77, v137
	v_mov_b32_e32 v76, v137
	v_mov_b32_e32 v75, v137
	v_mov_b32_e32 v74, v137
	v_mov_b32_e32 v125, v137
	v_mov_b32_e32 v124, v137
	v_mov_b32_e32 v123, v137
	v_mov_b32_e32 v122, v137
	v_mov_b32_e32 v121, v137
	v_mov_b32_e32 v120, v137
	v_mov_b32_e32 v119, v137
	v_mov_b32_e32 v118, v137
	v_mov_b32_e32 v105, v137
	v_mov_b32_e32 v104, v137
	v_mov_b32_e32 v103, v137
	v_mov_b32_e32 v102, v137
	v_mov_b32_e32 v101, v137
	v_mov_b32_e32 v100, v137
	v_mov_b32_e32 v99, v137
	v_mov_b32_e32 v98, v137
	v_mov_b32_e32 v89, v137
	v_mov_b32_e32 v88, v137
	v_mov_b32_e32 v87, v137
	v_mov_b32_e32 v86, v137
	v_mov_b32_e32 v85, v137
	v_mov_b32_e32 v84, v137
	v_mov_b32_e32 v83, v137
	v_mov_b32_e32 v82, v137
	v_mov_b32_e32 v73, v137
	v_mov_b32_e32 v72, v137
	v_mov_b32_e32 v71, v137
	v_mov_b32_e32 v70, v137
	v_mov_b32_e32 v69, v137
	v_mov_b32_e32 v68, v137
	v_mov_b32_e32 v67, v137
	v_mov_b32_e32 v66, v137
	v_mov_b32_e32 v65, v137
	v_mov_b32_e32 v64, v137
	v_mov_b32_e32 v63, v137
	v_mov_b32_e32 v62, v137
	v_mov_b32_e32 v61, v137
	v_mov_b32_e32 v60, v137
	v_mov_b32_e32 v59, v137
	s_nop 0
	v_mov_b32_e32 v58, v137
	v_mov_b32_e32 v49, v137
	v_mov_b32_e32 v48, v137
	v_mov_b32_e32 v47, v137
	v_mov_b32_e32 v46, v137
	v_mov_b32_e32 v45, v137
	v_mov_b32_e32 v44, v137
	v_mov_b32_e32 v43, v137
	v_mov_b32_e32 v42, v137
	v_mov_b32_e32 v33, v137
	v_mov_b32_e32 v32, v137
	v_mov_b32_e32 v31, v137
	v_mov_b32_e32 v30, v137
	v_mov_b32_e32 v29, v137
	v_mov_b32_e32 v28, v137
	v_mov_b32_e32 v27, v137
	v_mov_b32_e32 v26, v137
	v_mov_b32_e32 v17, v137
	v_mov_b32_e32 v16, v137
	v_mov_b32_e32 v15, v137
	v_mov_b32_e32 v14, v137
	v_mov_b32_e32 v13, v137
	v_mov_b32_e32 v12, v137
	v_mov_b32_e32 v11, v137
	v_mov_b32_e32 v10, v137
	v_mov_b32_e32 v57, v137
	v_mov_b32_e32 v56, v137
	v_mov_b32_e32 v55, v137
	v_mov_b32_e32 v54, v137
	v_mov_b32_e32 v53, v137
	v_mov_b32_e32 v52, v137
	v_mov_b32_e32 v51, v137
	v_mov_b32_e32 v50, v137
	v_mov_b32_e32 v41, v137
	v_mov_b32_e32 v40, v137
	v_mov_b32_e32 v39, v137
	v_mov_b32_e32 v38, v137
	v_mov_b32_e32 v37, v137
	v_mov_b32_e32 v36, v137
	v_mov_b32_e32 v35, v137
	v_mov_b32_e32 v34, v137
	v_mov_b32_e32 v25, v137
	v_mov_b32_e32 v24, v137
	v_mov_b32_e32 v23, v137
	v_mov_b32_e32 v22, v137
	v_mov_b32_e32 v21, v137
	v_mov_b32_e32 v20, v137
	v_mov_b32_e32 v19, v137
	v_mov_b32_e32 v18, v137
	v_mov_b32_e32 v9, v137
	v_mov_b32_e32 v8, v137
	v_mov_b32_e32 v7, v137
	v_mov_b32_e32 v6, v137
	v_mov_b32_e32 v5, v137
	v_mov_b32_e32 v4, v137
	v_mov_b32_e32 v3, v137
	v_mov_b32_e32 v2, v137
	s_cbranch_vccz .LBB0_698
	s_and_b64 vcc, exec, s[48:49]
	s_cbranch_vccnz .LBB0_701

;     __host__ __device__ bool next(int i, Unit& u) const { const int P = (i >> 1) * G + c; if (P >= 256) return false; u.pm = P >> 3; u.pn = (P & 7) + 8 * (i & 1); return true; }
; template <class Epi, class Sched, bool ALIGN_EPI = false, bool SP2 = false>
; __device__ __forceinline__ void gemm_phase(PG8_LAS unsigned char* lds, const Gemm g, const Sched& S, const Epi& E, const int wv) {
;     ...
;         const bool has_next = S.next(ui + 1, nxt);
;         const char* nA = has_next ? (const char*)g.A + (size_t)nxt.pm * tstepA + (g.amod ? (size_t)(nxt.pn % g.amod) * K * 2 : (size_t)0) : cA; const char* nB = has_next ? (const char*)g.Bt + (size_t)nxt.pn * tstepB : cB;
;     ...
; #pragma unroll
;         for (int a = 0; a < 2; ++a)
; #pragma unroll
;             for (int b = 0; b < 2; ++b)
; #pragma unroll
;                 for (int m = 0; m < 4; ++m)
; #pragma unroll
;                     for (int n = 0; n < 2; ++n) acc[a][b][m][n] = (f32x4){0.f, 0.f, 0.f, 0.f};
;         cur = nxt; cA = nA; cB = nB; ++ui;
.LBB0_1072:
	s_ashr_i32 s17, s16, 31
	s_lshl_b64 s[24:25], s[16:17], 20
	s_add_u32 s24, s43, s24
	v_mov_b32_e32 v133, 0
	s_addc_u32 s25, s44, s25
	s_andn2_b64 vcc, exec, s[12:13]
	v_mov_b32_e32 v132, v133
	v_mov_b32_e32 v131, v133
	v_mov_b32_e32 v130, v133
	v_mov_b32_e32 v129, v133
	v_mov_b32_e32 v128, v133
	v_mov_b32_e32 v127, v133
	v_mov_b32_e32 v126, v133
	v_mov_b32_e32 v117, v133
	v_mov_b32_e32 v116, v133
	v_mov_b32_e32 v115, v133
	v_mov_b32_e32 v114, v133
	v_mov_b32_e32 v113, v133
	v_mov_b32_e32 v112, v133
	v_mov_b32_e32 v111, v133
	v_mov_b32_e32 v110, v133
	v_mov_b32_e32 v101, v133
	v_mov_b32_e32 v100, v133
	v_mov_b32_e32 v99, v133
	v_mov_b32_e32 v98, v133
	s_nop 0
	v_mov_b32_e32 v97, v133
	v_mov_b32_e32 v96, v133
	v_mov_b32_e32 v95, v133
	v_mov_b32_e32 v94, v133
	v_mov_b32_e32 v85, v133
	v_mov_b32_e32 v84, v133
	v_mov_b32_e32 v83, v133
	v_mov_b32_e32 v82, v133
	v_mov_b32_e32 v81, v133
	v_mov_b32_e32 v80, v133
	v_mov_b32_e32 v79, v133
	v_mov_b32_e32 v78, v133
	v_mov_b32_e32 v125, v133
	v_mov_b32_e32 v124, v133
	v_mov_b32_e32 v123, v133
	v_mov_b32_e32 v122, v133
	v_mov_b32_e32 v121, v133
	v_mov_b32_e32 v120, v133
	v_mov_b32_e32 v119, v133
	v_mov_b32_e32 v118, v133
	v_mov_b32_e32 v109, v133
	v_mov_b32_e32 v108, v133
	v_mov_b32_e32 v107, v133
	v_mov_b32_e32 v106, v133
	v_mov_b32_e32 v105, v133
	v_mov_b32_e32 v104, v133
	v_mov_b32_e32 v103, v133
	v_mov_b32_e32 v102, v133
	v_mov_b32_e32 v93, v133
	v_mov_b32_e32 v92, v133
	v_mov_b32_e32 v91, v133
	v_mov_b32_e32 v90, v133
	v_mov_b32_e32 v89, v133
	v_mov_b32_e32 v88, v133
	v_mov_b32_e32 v87, v133
	v_mov_b32_e32 v86, v133
	v_mov_b32_e32 v77, v133
	v_mov_b32_e32 v76, v133
	v_mov_b32_e32 v75, v133
	v_mov_b32_e32 v74, v133
	v_mov_b32_e32 v73, v133
	v_mov_b32_e32 v72, v133
	v_mov_b32_e32 v71, v133
	v_mov_b32_e32 v70, v133
	v_mov_b32_e32 v69, v133
	v_mov_b32_e32 v68, v133
	v_mov_b32_e32 v67, v133
	v_mov_b32_e32 v66, v133
	v_mov_b32_e32 v65, v133
	v_mov_b32_e32 v64, v133
	v_mov_b32_e32 v63, v133
	v_mov_b32_e32 v62, v133
	v_mov_b32_e32 v53, v133
	v_mov_b32_e32 v52, v133
	v_mov_b32_e32 v51, v133
	v_mov_b32_e32 v50, v133
	v_mov_b32_e32 v49, v133
	v_mov_b32_e32 v48, v133
	v_mov_b32_e32 v47, v133
	v_mov_b32_e32 v46, v133
	v_mov_b32_e32 v37, v133
	v_mov_b32_e32 v36, v133
	v_mov_b32_e32 v35, v133
	v_mov_b32_e32 v34, v133
	v_mov_b32_e32 v33, v133
	v_mov_b32_e32 v32, v133
	v_mov_b32_e32 v31, v133
	v_mov_b32_e32 v30, v133
	v_mov_b32_e32 v21, v133
	v_mov_b32_e32 v20, v133
	v_mov_b32_e32 v19, v133
	v_mov_b32_e32 v18, v133
	v_mov_b32_e32 v17, v133
	v_mov_b32_e32 v16, v133
	v_mov_b32_e32 v15, v133
	v_mov_b32_e32 v14, v133
	v_mov_b32_e32 v61, v133
	v_mov_b32_e32 v60, v133
	v_mov_b32_e32 v59, v133
	v_mov_b32_e32 v58, v133
	v_mov_b32_e32 v57, v133
	v_mov_b32_e32 v56, v133
	v_mov_b32_e32 v55, v133
	v_mov_b32_e32 v54, v133
	v_mov_b32_e32 v45, v133
	v_mov_b32_e32 v44, v133
	v_mov_b32_e32 v43, v133
	v_mov_b32_e32 v42, v133
	v_mov_b32_e32 v41, v133
	v_mov_b32_e32 v40, v133
	v_mov_b32_e32 v39, v133
	v_mov_b32_e32 v38, v133
	v_mov_b32_e32 v29, v133
	v_mov_b32_e32 v28, v133
	v_mov_b32_e32 v27, v133
	v_mov_b32_e32 v26, v133
	v_mov_b32_e32 v25, v133
	v_mov_b32_e32 v24, v133
	v_mov_b32_e32 v23, v133
	v_mov_b32_e32 v22, v133
	v_mov_b32_e32 v13, v133
	v_mov_b32_e32 v12, v133
	v_mov_b32_e32 v11, v133
	v_mov_b32_e32 v10, v133
	v_mov_b32_e32 v9, v133
	v_mov_b32_e32 v8, v133
	v_mov_b32_e32 v7, v133
	v_mov_b32_e32 v6, v133
	s_cbranch_vccnz .LBB0_1076
	s_and_b64 s[40:41], s[40:41], exec
	s_cselect_b32 s17, s25, s29
	s_cselect_b32 s40, s24, s28
	s_add_u32 s28, s28, 0x80080
	s_addc_u32 s29, s29, 0
	s_add_u32 s41, s30, 0x100
	v_mov_b32_e32 v6, 0
	s_addc_u32 s62, s31, 0
	s_mov_b32 s30, 0
	v_mov_b32_e32 v7, v6
	v_mov_b32_e32 v8, v6
	v_mov_b32_e32 v9, v6
	v_mov_b32_e32 v10, v6
	v_mov_b32_e32 v11, v6
	v_mov_b32_e32 v12, v6
	v_mov_b32_e32 v13, v6
	v_mov_b32_e32 v22, v6
	v_mov_b32_e32 v23, v6
	v_mov_b32_e32 v24, v6
	v_mov_b32_e32 v25, v6
	v_mov_b32_e32 v26, v6
	v_mov_b32_e32 v27, v6
	v_mov_b32_e32 v28, v6
	v_mov_b32_e32 v29, v6
	v_mov_b32_e32 v38, v6
	v_mov_b32_e32 v39, v6
	v_mov_b32_e32 v40, v6
	v_mov_b32_e32 v41, v6
	v_mov_b32_e32 v42, v6
	v_mov_b32_e32 v43, v6
	v_mov_b32_e32 v44, v6
	v_mov_b32_e32 v45, v6
	v_mov_b32_e32 v54, v6
	v_mov_b32_e32 v55, v6
	v_mov_b32_e32 v56, v6
	v_mov_b32_e32 v57, v6
	v_mov_b32_e32 v58, v6
	v_mov_b32_e32 v59, v6
	v_mov_b32_e32 v60, v6
	v_mov_b32_e32 v61, v6
	v_mov_b32_e32 v14, v6
	v_mov_b32_e32 v15, v6
	v_mov_b32_e32 v16, v6
	v_mov_b32_e32 v17, v6
	v_mov_b32_e32 v18, v6
	v_mov_b32_e32 v19, v6
	v_mov_b32_e32 v20, v6
	v_mov_b32_e32 v21, v6
	v_mov_b32_e32 v30, v6
	v_mov_b32_e32 v31, v6
	v_mov_b32_e32 v32, v6
	v_mov_b32_e32 v33, v6
	v_mov_b32_e32 v34, v6
	v_mov_b32_e32 v35, v6
	v_mov_b32_e32 v36, v6
	v_mov_b32_e32 v37, v6
	v_mov_b32_e32 v46, v6
	v_mov_b32_e32 v47, v6
	v_mov_b32_e32 v48, v6
	v_mov_b32_e32 v49, v6
	v_mov_b32_e32 v50, v6
	v_mov_b32_e32 v51, v6
	v_mov_b32_e32 v52, v6
	v_mov_b32_e32 v53, v6
	v_mov_b32_e32 v62, v6
	v_mov_b32_e32 v63, v6
	v_mov_b32_e32 v64, v6
	v_mov_b32_e32 v65, v6
	v_mov_b32_e32 v66, v6
	v_mov_b32_e32 v67, v6
	v_mov_b32_e32 v68, v6
	v_mov_b32_e32 v69, v6
	v_mov_b32_e32 v70, v6
	v_mov_b32_e32 v71, v6
	v_mov_b32_e32 v72, v6
	v_mov_b32_e32 v73, v6
	v_mov_b32_e32 v74, v6
	v_mov_b32_e32 v75, v6
	v_mov_b32_e32 v76, v6
	v_mov_b32_e32 v77, v6
	v_mov_b32_e32 v86, v6
	v_mov_b32_e32 v87, v6
	v_mov_b32_e32 v88, v6
	v_mov_b32_e32 v89, v6
	v_mov_b32_e32 v90, v6
	v_mov_b32_e32 v91, v6
	v_mov_b32_e32 v92, v6
	v_mov_b32_e32 v93, v6
	v_mov_b32_e32 v102, v6
	v_mov_b32_e32 v103, v6
	v_mov_b32_e32 v104, v6
	v_mov_b32_e32 v105, v6
	v_mov_b32_e32 v106, v6
	v_mov_b32_e32 v107, v6
	v_mov_b32_e32 v108, v6
	v_mov_b32_e32 v109, v6
	v_mov_b32_e32 v118, v6
	v_mov_b32_e32 v119, v6
	v_mov_b32_e32 v120, v6
	v_mov_b32_e32 v121, v6
	v_mov_b32_e32 v122, v6
	v_mov_b32_e32 v123, v6
	v_mov_b32_e32 v124, v6
	v_mov_b32_e32 v125, v6
	v_mov_b32_e32 v78, v6
	v_mov_b32_e32 v79, v6
	v_mov_b32_e32 v80, v6
	v_mov_b32_e32 v81, v6
	v_mov_b32_e32 v82, v6
	v_mov_b32_e32 v83, v6
	v_mov_b32_e32 v84, v6
	v_mov_b32_e32 v85, v6
	v_mov_b32_e32 v94, v6
	v_mov_b32_e32 v95, v6
	v_mov_b32_e32 v96, v6
	v_mov_b32_e32 v97, v6
	v_mov_b32_e32 v98, v6
	v_mov_b32_e32 v99, v6
	v_mov_b32_e32 v100, v6
	v_mov_b32_e32 v101, v6
	v_mov_b32_e32 v110, v6
	v_mov_b32_e32 v111, v6
	v_mov_b32_e32 v112, v6
	v_mov_b32_e32 v113, v6
	v_mov_b32_e32 v114, v6
	v_mov_b32_e32 v115, v6
	v_mov_b32_e32 v116, v6
	v_mov_b32_e32 v117, v6
	v_mov_b32_e32 v126, v6
	v_mov_b32_e32 v127, v6
	v_mov_b32_e32 v128, v6
	v_mov_b32_e32 v129, v6
	v_mov_b32_e32 v130, v6
	v_mov_b32_e32 v131, v6
	v_mov_b32_e32 v132, v6
	v_mov_b32_e32 v133, v6
